# GDN: the remaining 8 rsqrtf denormal guards (paired e64/pk_mul variant in the q/k l2-norm) removed as well
# speedup vs baseline: 1.0075x; 1.0014x over previous
; DI float bflo(unsigned w) { return __uint_as_float(w << 16); }
; DI float bfhi(unsigned w) { return __uint_as_float(w & 0xffff0000u); }
; DI float siluf_(float x) { return x * __builtin_amdgcn_rcpf(1.0f + __expf(-x)); }
; DI float wave_sum(float v) { v = row16_sum(v); return (rdlane(v, 0) + rdlane(v, 16)) + (rdlane(v, 32) + rdlane(v, 48)); }
; DI void gdn_unit(const Params& P, bf16_t* proj, const float* gb, int b, int h, LAS unsigned char* lds) {
;     ...
;         for (int w = 0; w < 3; ++w) {
;             const f32x2 (&cw)[4] = cwr[w];
;             const unsigned (&raw)[11] = rawq[w];
;             float o0[8], o1[8];
; #pragma unroll
;             for (int i = 0; i < 8; ++i) {
;                 float a0 = 0.f, a1 = 0.f;
; #pragma unroll
;                 for (int j = 0; j < 4; ++j) { a0 += cw[j][0] * bflo(raw[i + j]); a1 += cw[j][1] * bfhi(raw[i + j]); }
;                 a0 = siluf_(a0); a1 = siluf_(a1);
;                 if (w < 2) {
;                     const float ss = wave_sum(a0 * a0 + a1 * a1);
;                     const float rs = rsqrtf(ss + 1e-6f) * (w == 0 ? 0.08838834764831845f : 1.0f);
;                     a0 *= rs; a1 *= rs;
;                 }
;                 o0[i] = a0; o1[i] = a1;
.LBB0_423:
	v_and_b32_e32 v63, 0xffff0000, v136
	v_lshlrev_b32_e32 v62, 16, v136
	v_and_b32_e32 v57, 0xffff0000, v157
	v_lshlrev_b32_e32 v56, 16, v157
	v_pk_fma_f32 v[62:63], v[68:69], v[62:63], 0 op_sel_hi:[1,1,0]
	v_and_b32_e32 v59, 0xffff0000, v156
	v_lshlrev_b32_e32 v58, 16, v156
	v_pk_fma_f32 v[110:111], v[68:69], v[56:57], 0 op_sel_hi:[1,1,0]
	v_pk_fma_f32 v[56:57], v[70:71], v[56:57], v[62:63]
	v_and_b32_e32 v61, 0xffff0000, v160
	v_lshlrev_b32_e32 v60, 16, v160
	v_pk_fma_f32 v[56:57], v[72:73], v[58:59], v[56:57]
	v_pk_fma_f32 v[64:65], v[68:69], v[58:59], 0 op_sel_hi:[1,1,0]
	v_pk_fma_f32 v[56:57], v[74:75], v[60:61], v[56:57]
	v_pk_fma_f32 v[110:111], v[70:71], v[58:59], v[110:111]
	v_mul_f32_e32 v58, 0xbfb8aa3b, v57
	v_exp_f32_e32 v58, v58
	s_movk_i32 s0, 0x11c
	v_mul_lo_u32 v55, v67, s0
	s_mov_b32 s26, 0x800000
	v_add_f32_e32 v58, 1.0, v58
	v_rcp_f32_e32 v59, v58
	v_mul_f32_e32 v58, 0xbfb8aa3b, v56
	v_exp_f32_e32 v58, v58
	v_and_b32_e32 v53, 0xffff0000, v159
	v_lshlrev_b32_e32 v52, 16, v159
	v_pk_fma_f32 v[50:51], v[68:69], v[60:61], 0 op_sel_hi:[1,1,0]
	v_add_f32_e32 v58, 1.0, v58
	v_rcp_f32_e32 v58, v58
	v_pk_fma_f32 v[64:65], v[70:71], v[60:61], v[64:65]
	v_and_b32_e32 v49, 0xffff0000, v158
	v_lshlrev_b32_e32 v48, 16, v158
	v_pk_mul_f32 v[58:59], v[56:57], v[58:59]
	v_pk_fma_f32 v[46:47], v[68:69], v[52:53], 0 op_sel_hi:[1,1,0]
	v_pk_mul_f32 v[56:57], v[58:59], v[58:59]
	v_pk_fma_f32 v[50:51], v[70:71], v[52:53], v[50:51]
	v_add_f32_e32 v56, v57, v56
	v_and_b32_e32 v45, 0xffff0000, v176
	v_lshlrev_b32_e32 v44, 16, v176
	v_add_f32_dpp v56, v56, v56 quad_perm:[1,0,3,2] row_mask:0xf bank_mask:0xf bound_ctrl:1
	v_pk_fma_f32 v[42:43], v[68:69], v[48:49], 0 op_sel_hi:[1,1,0]
	v_pk_fma_f32 v[46:47], v[70:71], v[48:49], v[46:47]
	v_add_f32_dpp v56, v56, v56 quad_perm:[2,3,0,1] row_mask:0xf bank_mask:0xf bound_ctrl:1
	v_and_b32_e32 v33, 0xffff0000, v161
	v_lshlrev_b32_e32 v32, 16, v161
	v_add_f32_dpp v56, v56, v56 row_half_mirror row_mask:0xf bank_mask:0xf bound_ctrl:1
	v_pk_fma_f32 v[40:41], v[68:69], v[44:45], 0 op_sel_hi:[1,1,0]
	v_pk_fma_f32 v[42:43], v[70:71], v[44:45], v[42:43]
	v_add_f32_dpp v56, v56, v56 row_mirror row_mask:0xf bank_mask:0xf bound_ctrl:1
	v_and_b32_e32 v35, 0xffff0000, v179
	v_readlane_b32 s2, v56, 16
	v_readlane_b32 s3, v56, 48
	v_readlane_b32 s0, v56, 0
	v_readlane_b32 s1, v56, 32
	v_mov_b32_e32 v56, s2
	v_mov_b32_e32 v57, s3
	v_pk_add_f32 v[56:57], s[0:1], v[56:57]
	v_lshlrev_b32_e32 v34, 16, v179
	v_add_f32_e32 v56, v56, v57
	v_add_f32_e32 v56, 0x358637bd, v56
	s_nop 0
	s_nop 0
	v_pk_fma_f32 v[42:43], v[72:73], v[32:33], v[42:43]
	s_nop 0
	v_rsq_f32_e32 v56, v56
	v_pk_fma_f32 v[42:43], v[74:75], v[34:35], v[42:43]
	v_pk_fma_f32 v[40:41], v[70:71], v[32:33], v[40:41]
	v_and_b32_e32 v37, 0xffff0000, v178
	s_nop 0
	v_mul_f32_e32 v56, 0x3db504f3, v56
	v_mul_f32_e32 v57, v58, v56
	v_mul_f32_e32 v56, v59, v56
	v_pk_fma_f32 v[58:59], v[72:73], v[60:61], v[110:111]
	v_lshlrev_b32_e32 v36, 16, v178
	v_pk_fma_f32 v[58:59], v[74:75], v[52:53], v[58:59]
	v_pk_fma_f32 v[52:53], v[72:73], v[52:53], v[64:65]
	v_mul_f32_e32 v60, 0xbfb8aa3b, v59
	v_exp_f32_e32 v60, v60
	v_pk_fma_f32 v[52:53], v[74:75], v[48:49], v[52:53]
	v_pk_fma_f32 v[48:49], v[72:73], v[48:49], v[50:51]
	v_pk_fma_f32 v[40:41], v[72:73], v[34:35], v[40:41]
	v_add_f32_e32 v60, 1.0, v60
	v_rcp_f32_e32 v61, v60
	v_mul_f32_e32 v60, 0xbfb8aa3b, v58
	v_exp_f32_e32 v60, v60
	v_pk_fma_f32 v[48:49], v[74:75], v[44:45], v[48:49]
	v_pk_fma_f32 v[44:45], v[72:73], v[44:45], v[46:47]
	v_mul_f32_e32 v50, 0xbfb8aa3b, v49
	v_add_f32_e32 v60, 1.0, v60
	v_rcp_f32_e32 v60, v60
	v_exp_f32_e32 v50, v50
	v_pk_fma_f32 v[44:45], v[74:75], v[32:33], v[44:45]
	v_pk_fma_f32 v[40:41], v[74:75], v[36:37], v[40:41]
	v_pk_mul_f32 v[60:61], v[58:59], v[60:61]
	v_add_f32_e32 v50, 1.0, v50
	v_pk_mul_f32 v[58:59], v[60:61], v[60:61]
	v_rcp_f32_e32 v51, v50
	v_add_f32_e32 v58, v59, v58
	v_mul_f32_e32 v50, 0xbfb8aa3b, v48
	v_exp_f32_e32 v50, v50
	v_add_f32_dpp v58, v58, v58 quad_perm:[1,0,3,2] row_mask:0xf bank_mask:0xf bound_ctrl:1
	v_mul_f32_e32 v46, 0xbfb8aa3b, v45
	v_exp_f32_e32 v46, v46
	v_add_f32_dpp v58, v58, v58 quad_perm:[2,3,0,1] row_mask:0xf bank_mask:0xf bound_ctrl:1
	v_add_f32_e32 v50, 1.0, v50
	v_rcp_f32_e32 v50, v50
	v_add_f32_dpp v58, v58, v58 row_half_mirror row_mask:0xf bank_mask:0xf bound_ctrl:1
	v_add_f32_e32 v46, 1.0, v46
	v_rcp_f32_e32 v47, v46
	v_add_f32_dpp v58, v58, v58 row_mirror row_mask:0xf bank_mask:0xf bound_ctrl:1
	v_mul_f32_e32 v46, 0xbfb8aa3b, v44
	v_readlane_b32 s2, v58, 16
	v_readlane_b32 s3, v58, 48
	v_readlane_b32 s0, v58, 0
	v_readlane_b32 s1, v58, 32
	v_mov_b32_e32 v58, s2
	v_mov_b32_e32 v59, s3
	v_pk_add_f32 v[58:59], s[0:1], v[58:59]
	v_exp_f32_e32 v46, v46
	v_add_f32_e32 v58, v58, v59
	v_add_f32_e32 v58, 0x358637bd, v58
	s_nop 0
	s_nop 0
	v_pk_mul_f32 v[48:49], v[48:49], v[50:51]
	s_nop 0
	v_rsq_f32_e32 v58, v58
	v_pk_mul_f32 v[50:51], v[48:49], v[48:49]
	v_add_f32_e32 v46, 1.0, v46
	v_add_f32_e32 v50, v51, v50
	s_nop 0
	s_nop 0
	v_mul_f32_e32 v58, 0x3db504f3, v58
	v_mul_f32_e32 v59, v60, v58
	v_mul_f32_e32 v60, 0xbfb8aa3b, v53
	v_exp_f32_e32 v60, v60
	v_mul_f32_e32 v58, v61, v58
	v_add_f32_dpp v50, v50, v50 quad_perm:[1,0,3,2] row_mask:0xf bank_mask:0xf bound_ctrl:1
	v_rcp_f32_e32 v46, v46
	v_add_f32_e32 v60, 1.0, v60
	v_rcp_f32_e32 v61, v60
	v_mul_f32_e32 v60, 0xbfb8aa3b, v52
	v_exp_f32_e32 v60, v60
	v_add_f32_dpp v50, v50, v50 quad_perm:[2,3,0,1] row_mask:0xf bank_mask:0xf bound_ctrl:1
	v_pk_mul_f32 v[44:45], v[44:45], v[46:47]
	v_pk_fma_f32 v[32:33], v[68:69], v[32:33], 0 op_sel_hi:[1,1,0]
	v_add_f32_e32 v60, 1.0, v60
	v_rcp_f32_e32 v60, v60
; DI float bflo(unsigned w) { return __uint_as_float(w << 16); }
; DI float bfhi(unsigned w) { return __uint_as_float(w & 0xffff0000u); }
; DI float siluf_(float x) { return x * __builtin_amdgcn_rcpf(1.0f + __expf(-x)); }
; DI float wave_sum(float v) { v = row16_sum(v); return (rdlane(v, 0) + rdlane(v, 16)) + (rdlane(v, 32) + rdlane(v, 48)); }
; DI void gdn_unit(const Params& P, bf16_t* proj, const float* gb, int b, int h, LAS unsigned char* lds) {
;     ...
;             for (int i = 0; i < 8; ++i) {
;                 float a0 = 0.f, a1 = 0.f;
; #pragma unroll
;                 for (int j = 0; j < 4; ++j) { a0 += cw[j][0] * bflo(raw[i + j]); a1 += cw[j][1] * bfhi(raw[i + j]); }
;                 a0 = siluf_(a0); a1 = siluf_(a1);
;                 if (w < 2) {
;                     const float ss = wave_sum(a0 * a0 + a1 * a1);
;                     const float rs = rsqrtf(ss + 1e-6f) * (w == 0 ? 0.08838834764831845f : 1.0f);
;                     a0 *= rs; a1 *= rs;
;                 }
;                 o0[i] = a0; o1[i] = a1;
	v_add_f32_dpp v50, v50, v50 row_half_mirror row_mask:0xf bank_mask:0xf bound_ctrl:1
	v_pk_mul_f32 v[46:47], v[44:45], v[44:45]
	v_pk_fma_f32 v[32:33], v[70:71], v[34:35], v[32:33]
	v_pk_mul_f32 v[60:61], v[52:53], v[60:61]
	v_add_f32_dpp v50, v50, v50 row_mirror row_mask:0xf bank_mask:0xf bound_ctrl:1
	v_pk_mul_f32 v[52:53], v[60:61], v[60:61]
	v_add_f32_e32 v46, v47, v46
	v_add_f32_e32 v52, v53, v52
	v_and_b32_e32 v39, 0xffff0000, v182
	v_add_f32_dpp v46, v46, v46 quad_perm:[1,0,3,2] row_mask:0xf bank_mask:0xf bound_ctrl:1
	v_add_f32_dpp v52, v52, v52 quad_perm:[1,0,3,2] row_mask:0xf bank_mask:0xf bound_ctrl:1
	v_lshlrev_b32_e32 v38, 16, v182
	v_add_f32_dpp v46, v46, v46 quad_perm:[2,3,0,1] row_mask:0xf bank_mask:0xf bound_ctrl:1
	v_add_f32_dpp v52, v52, v52 quad_perm:[2,3,0,1] row_mask:0xf bank_mask:0xf bound_ctrl:1
	v_pk_fma_f32 v[32:33], v[72:73], v[36:37], v[32:33]
	v_add_f32_dpp v46, v46, v46 row_half_mirror row_mask:0xf bank_mask:0xf bound_ctrl:1
	v_add_f32_dpp v52, v52, v52 row_half_mirror row_mask:0xf bank_mask:0xf bound_ctrl:1
	v_pk_fma_f32 v[32:33], v[74:75], v[38:39], v[32:33]
	v_add_f32_dpp v46, v46, v46 row_mirror row_mask:0xf bank_mask:0xf bound_ctrl:1
	v_add_f32_dpp v52, v52, v52 row_mirror row_mask:0xf bank_mask:0xf bound_ctrl:1
	v_mul_f32_e32 v34, 0xbfb8aa3b, v33
	v_readlane_b32 s2, v52, 16
	v_readlane_b32 s3, v52, 48
	v_readlane_b32 s0, v52, 0
	v_readlane_b32 s1, v52, 32
	v_mov_b32_e32 v52, s2
	v_mov_b32_e32 v53, s3
	v_pk_add_f32 v[52:53], s[0:1], v[52:53]
	v_readlane_b32 s2, v50, 16
	v_add_f32_e32 v52, v52, v53
	v_add_f32_e32 v52, 0x358637bd, v52
	s_nop 0
	s_nop 0
	v_readlane_b32 s3, v50, 48
	s_nop 0
	v_rsq_f32_e32 v52, v52
	v_readlane_b32 s0, v50, 0
	v_readlane_b32 s1, v50, 32
	v_mov_b32_e32 v50, s2
	v_mov_b32_e32 v51, s3
	v_pk_add_f32 v[50:51], s[0:1], v[50:51]
	s_nop 0
	v_add_f32_e32 v50, v50, v51
	v_add_f32_e32 v50, 0x358637bd, v50
	s_nop 0
	s_nop 0
	s_nop 0
	v_readlane_b32 s2, v46, 16
	s_nop 0
	v_rsq_f32_e32 v50, v50
	v_readlane_b32 s3, v46, 48
	v_readlane_b32 s0, v46, 0
	v_readlane_b32 s1, v46, 32
	v_mov_b32_e32 v46, s2
	v_mov_b32_e32 v47, s3
	v_pk_add_f32 v[46:47], s[0:1], v[46:47]
	s_nop 0
	v_add_f32_e32 v46, v46, v47
	v_add_f32_e32 v46, 0x358637bd, v46
	s_nop 0
	s_nop 0
	s_nop 0
	v_exp_f32_e32 v34, v34
	s_nop 0
	v_rsq_f32_e32 v46, v46
	v_bfe_u32 v36, v58, 16, 1
	v_add_f32_e32 v34, 1.0, v34
	v_rcp_f32_e32 v35, v34
	s_nop 0
	s_nop 0
	v_mul_f32_e32 v46, 0x3db504f3, v46
	v_mul_f32_e32 v47, v44, v46
	v_mul_f32_e32 v44, 0xbfb8aa3b, v43
	v_exp_f32_e32 v44, v44
	v_mul_f32_e32 v46, v45, v46
	v_mul_f32_e32 v34, 0xbfb8aa3b, v32
	v_exp_f32_e32 v34, v34
	v_add_f32_e32 v44, 1.0, v44
	v_rcp_f32_e32 v45, v44
	v_mul_f32_e32 v44, 0xbfb8aa3b, v42
	v_exp_f32_e32 v44, v44
	v_add_f32_e32 v34, 1.0, v34
	v_rcp_f32_e32 v34, v34
	v_mul_f32_e32 v52, 0x3db504f3, v52
	v_add_f32_e32 v44, 1.0, v44
	v_rcp_f32_e32 v44, v44
	v_pk_mul_f32 v[32:33], v[32:33], v[34:35]
	v_add3_u32 v36, v58, v36, s68
	v_pk_mul_f32 v[34:35], v[32:33], v[32:33]
	v_pk_mul_f32 v[42:43], v[42:43], v[44:45]
	v_add_f32_e32 v34, v35, v34
	v_pk_mul_f32 v[44:45], v[42:43], v[42:43]
	v_mul_f32_e32 v53, v60, v52
	v_add_f32_e32 v44, v45, v44
	v_add_f32_dpp v34, v34, v34 quad_perm:[1,0,3,2] row_mask:0xf bank_mask:0xf bound_ctrl:1
	v_mul_f32_e32 v52, v61, v52
	v_add_f32_dpp v44, v44, v44 quad_perm:[1,0,3,2] row_mask:0xf bank_mask:0xf bound_ctrl:1
	v_add_f32_dpp v34, v34, v34 quad_perm:[2,3,0,1] row_mask:0xf bank_mask:0xf bound_ctrl:1
	v_mul_f32_e32 v50, 0x3db504f3, v50
	v_add_f32_dpp v44, v44, v44 quad_perm:[2,3,0,1] row_mask:0xf bank_mask:0xf bound_ctrl:1
	v_add_f32_dpp v34, v34, v34 row_half_mirror row_mask:0xf bank_mask:0xf bound_ctrl:1
	v_mul_f32_e32 v48, v48, v50
	v_add_f32_dpp v44, v44, v44 row_half_mirror row_mask:0xf bank_mask:0xf bound_ctrl:1
	v_add_f32_dpp v34, v34, v34 row_mirror row_mask:0xf bank_mask:0xf bound_ctrl:1
	v_mul_f32_e32 v49, v49, v50
	v_add_f32_dpp v44, v44, v44 row_mirror row_mask:0xf bank_mask:0xf bound_ctrl:1
	v_and_b32_e32 v50, 0xffff0000, v181
	v_readlane_b32 s2, v44, 16
	v_readlane_b32 s3, v44, 48
	v_readlane_b32 s0, v44, 0
	v_readlane_b32 s1, v44, 32
	v_mov_b32_e32 v44, s2
	v_mov_b32_e32 v45, s3
	v_pk_add_f32 v[44:45], s[0:1], v[44:45]
	v_lshlrev_b32_e32 v60, 16, v180
	v_add_f32_e32 v44, v44, v45
	v_add_f32_e32 v44, 0x358637bd, v44
	s_nop 0
	s_nop 0
	v_lshlrev_b32_e32 v38, 16, v184
	s_nop 0
	v_rsq_f32_e32 v44, v44
	v_lshlrev_b32_e32 v62, 16, v177
	v_mov_b32_e32 v63, v60
	v_lshlrev_b32_e32 v58, 16, v181
	s_nop 0
	s_nop 0
	v_mul_f32_e32 v44, 0x3db504f3, v44
	v_mul_f32_e32 v45, v42, v44
	v_mul_f32_e32 v42, 0xbfb8aa3b, v41
	v_exp_f32_e32 v42, v42
	v_mul_f32_e32 v44, v43, v44
	v_pk_fma_f32 v[62:63], v[98:99], v[62:63], 0 op_sel_hi:[1,1,0]
	v_lshlrev_b32_e32 v61, 16, v183
	v_add_f32_e32 v42, 1.0, v42
	v_rcp_f32_e32 v43, v42
	v_mul_f32_e32 v42, 0xbfb8aa3b, v40
	v_exp_f32_e32 v42, v42
	v_lshlrev_b32_e32 v39, 16, v186
	s_mov_b32 s76, 0x358637bd
	s_mov_b32 s78, 0x45800000
	v_add_f32_e32 v42, 1.0, v42
	v_rcp_f32_e32 v42, v42
	v_lshlrev_b32_e32 v37, 16, v190
	s_mov_b32 s72, 0x358637bd
	s_cmp_eq_u32 s14, 0xf80000
	v_pk_mul_f32 v[40:41], v[40:41], v[42:43]
	s_nop 0
	v_pk_mul_f32 v[42:43], v[40:41], v[40:41]
	s_nop 0
	v_add_f32_e32 v42, v43, v42
	s_nop 1
	v_add_f32_dpp v42, v42, v42 quad_perm:[1,0,3,2] row_mask:0xf bank_mask:0xf bound_ctrl:1
	s_nop 1
	v_add_f32_dpp v42, v42, v42 quad_perm:[2,3,0,1] row_mask:0xf bank_mask:0xf bound_ctrl:1
	s_nop 1
	v_add_f32_dpp v42, v42, v42 row_half_mirror row_mask:0xf bank_mask:0xf bound_ctrl:1
	s_nop 1
	v_add_f32_dpp v42, v42, v42 row_mirror row_mask:0xf bank_mask:0xf bound_ctrl:1
	s_nop 0
	v_readlane_b32 s2, v42, 16
; #define LAS __attribute__((address_space(3)))
; DI unsigned pk2(float lo, float hi) { return f2bf(lo) | (f2bf(hi) << 16); }
; DI float wave_sum(float v) { v = row16_sum(v); return (rdlane(v, 0) + rdlane(v, 16)) + (rdlane(v, 32) + rdlane(v, 48)); }
; DI void gdn_unit(const Params& P, bf16_t* proj, const float* gb, int b, int h, LAS unsigned char* lds) {
;     ...
;                 if (w < 2) {
;                     const float ss = wave_sum(a0 * a0 + a1 * a1);
;                     const float rs = rsqrtf(ss + 1e-6f) * (w == 0 ? 0.08838834764831845f : 1.0f);
;                     a0 *= rs; a1 *= rs;
;                 }
;                 o0[i] = a0; o1[i] = a1;
;             }
;             if (w < 2) {
;                 const int off = (w == 0) ? Q_OFF : K_OFF;
; #pragma unroll
;                 for (int i = 0; i < 8; ++i) *(LAS unsigned*)(lds + off + (wave * 8 + i) * 272 + lane * 4) = pk2(o0[i], o1[i]);
	v_readlane_b32 s3, v42, 48
	v_readlane_b32 s0, v42, 0
	v_readlane_b32 s1, v42, 32
	v_mov_b32_e32 v42, s2
	v_mov_b32_e32 v43, s3
	v_pk_add_f32 v[42:43], s[0:1], v[42:43]
	v_readlane_b32 s2, v34, 16
	v_add_f32_e32 v42, v42, v43
	v_add_f32_e32 v42, 0x358637bd, v42
	s_nop 0
	s_nop 0
	v_readlane_b32 s3, v34, 48
	s_nop 0
	v_rsq_f32_e32 v42, v42
	v_readlane_b32 s0, v34, 0
	v_readlane_b32 s1, v34, 32
	v_mov_b32_e32 v34, s2
	v_mov_b32_e32 v35, s3
	v_pk_add_f32 v[34:35], s[0:1], v[34:35]
	s_nop 0
	v_add_f32_e32 v34, v34, v35
	v_add_f32_e32 v34, 0x358637bd, v34
	s_nop 0
	s_nop 0
	s_nop 0
	v_mul_f32_e32 v42, 0x3db504f3, v42
	s_nop 0
	v_rsq_f32_e32 v34, v34
	v_mul_f32_e32 v40, v40, v42
	v_mul_f32_e32 v41, v41, v42
	v_and_b32_e32 v42, 0xffff0000, v184
	s_nop 0
	v_mul_f32_e32 v34, 0x3db504f3, v34
	v_mul_f32_e32 v32, v32, v34
	v_mul_f32_e32 v33, v33, v34
	s_nop 0
	v_cvt_pk_bf16_f32 v34, v57, v56
	v_cvt_pk_bf16_f32 v35, v59, v59
	v_lshrrev_b32_e32 v35, 16, v35
	v_add_u32_e32 v56, s92, v54
	v_and_or_b32 v35, v36, s39, v35
	ds_write2_b32 v56, v34, v35 offset1:68
	v_cvt_pk_bf16_f32 v34, v53, v52
	v_cvt_pk_bf16_f32 v35, v48, v49
	ds_write2_b32 v56, v34, v35 offset0:136 offset1:204
	v_cvt_pk_bf16_f32 v34, v47, v46
	v_cvt_pk_bf16_f32 v35, v45, v44
	v_add_u32_e32 v36, 0x400, v56
	ds_write2_b32 v36, v34, v35 offset0:16 offset1:84
	v_cvt_pk_bf16_f32 v34, v40, v41
	v_cvt_pk_bf16_f32 v32, v32, v33
	ds_write2_b32 v36, v34, v32 offset0:152 offset1:220
	v_and_b32_e32 v32, 0xffff0000, v177
	v_and_b32_e32 v48, 0xffff0000, v183
	v_mov_b32_e32 v33, v42
	v_and_b32_e32 v49, 0xffff0000, v186
	v_pk_fma_f32 v[32:33], v[76:77], v[32:33], 0 op_sel_hi:[1,1,0]
	v_mov_b32_e32 v51, v48
	v_and_b32_e32 v52, 0xffff0000, v180
	v_mov_b32_e32 v53, v49
	v_pk_fma_f32 v[32:33], v[92:93], v[50:51], v[32:33]
	v_and_b32_e32 v43, 0xffff0000, v185
	v_pk_fma_f32 v[32:33], v[94:95], v[52:53], v[32:33]
	v_mov_b32_e32 v51, v52
	v_pk_fma_f32 v[32:33], v[96:97], v[42:43], v[32:33]
	v_pk_fma_f32 v[50:51], v[76:77], v[50:51], 0 op_sel_hi:[1,1,0]
	v_mul_f32_e32 v34, 0xbfb8aa3b, v32
	v_exp_f32_e32 v34, v34
	v_mov_b32_e32 v53, v42
	v_mov_b32_e32 v64, v42
	v_mov_b32_e32 v65, v48
	v_add_f32_e32 v34, 1.0, v34
	v_rcp_f32_e32 v110, v34
	v_mul_f32_e32 v34, 0xbfb8aa3b, v33
	v_exp_f32_e32 v34, v34
	v_pk_fma_f32 v[50:51], v[92:93], v[52:53], v[50:51]
	v_mov_b32_e32 v59, v38
	v_pk_fma_f32 v[50:51], v[94:95], v[64:65], v[50:51]
	v_add_f32_e32 v34, 1.0, v34
	v_pk_fma_f32 v[50:51], v[96:97], v[48:49], v[50:51]
	v_rcp_f32_e32 v111, v34
	v_mul_f32_e32 v34, 0xbfb8aa3b, v50
	v_exp_f32_e32 v34, v34
	v_pk_fma_f32 v[62:63], v[78:79], v[58:59], v[62:63]
	v_pk_fma_f32 v[58:59], v[98:99], v[58:59], 0 op_sel_hi:[1,1,0]
	v_pk_fma_f32 v[62:63], v[80:81], v[60:61], v[62:63]
	v_add_f32_e32 v34, 1.0, v34
	v_rcp_f32_e32 v52, v34
	v_mul_f32_e32 v34, 0xbfb8aa3b, v51
	v_exp_f32_e32 v34, v34
	v_pk_fma_f32 v[62:63], v[82:83], v[38:39], v[62:63]
	v_pk_fma_f32 v[58:59], v[78:79], v[60:61], v[58:59]
	v_mul_f32_e32 v57, 0xbfb8aa3b, v62
	v_exp_f32_e32 v57, v57
	v_add_f32_e32 v34, 1.0, v34
	v_lshlrev_b32_e32 v35, 16, v185
	v_rcp_f32_e32 v53, v34
	v_mov_b32_e32 v34, v61
	v_pk_fma_f32 v[58:59], v[80:81], v[38:39], v[58:59]
	v_add_f32_e32 v57, 1.0, v57
	v_pk_fma_f32 v[58:59], v[82:83], v[34:35], v[58:59]
	v_rcp_f32_e32 v64, v57
	v_mul_f32_e32 v38, 0xbfb8aa3b, v58
	v_mul_f32_e32 v57, 0xbfb8aa3b, v63
	v_exp_f32_e32 v38, v38
	v_exp_f32_e32 v57, v57
	v_pk_mul_f32 v[32:33], v[32:33], v[110:111]
	v_pk_mul_f32 v[52:53], v[50:51], v[52:53]
	v_add_f32_e32 v38, 1.0, v38
	v_add_f32_e32 v57, 1.0, v57
	v_rcp_f32_e32 v60, v38
	v_mul_f32_e32 v38, 0xbfb8aa3b, v59
	v_rcp_f32_e32 v65, v57
	v_exp_f32_e32 v38, v38
	v_mov_b32_e32 v112, v33
	v_mov_b32_e32 v110, v53
	v_pk_mul_f32 v[62:63], v[62:63], v[64:65]
	v_add_f32_e32 v38, 1.0, v38
	v_mov_b32_e32 v64, v32
	v_mov_b32_e32 v65, v62
	v_rcp_f32_e32 v61, v38
	v_pk_mul_f32 v[64:65], v[64:65], v[64:65]
	v_mov_b32_e32 v111, v63
	v_add_f32_e32 v38, v64, v65
	v_pk_mul_f32 v[58:59], v[58:59], v[60:61]
	v_mov_b32_e32 v60, v52
	v_add_f32_dpp v38, v38, v38 quad_perm:[1,0,3,2] row_mask:0xf bank_mask:0xf bound_ctrl:1
	v_mov_b32_e32 v113, v59
	v_pk_mul_f32 v[112:113], v[112:113], v[112:113]
	v_add_f32_dpp v38, v38, v38 quad_perm:[2,3,0,1] row_mask:0xf bank_mask:0xf bound_ctrl:1
	v_mov_b32_e32 v61, v58
	v_pk_mul_f32 v[60:61], v[60:61], v[60:61]
	v_add_f32_dpp v38, v38, v38 row_half_mirror row_mask:0xf bank_mask:0xf bound_ctrl:1
	v_pk_mul_f32 v[110:111], v[110:111], v[110:111]
	v_and_b32_e32 v44, 0xffff0000, v187
	v_add_f32_dpp v38, v38, v38 row_mirror row_mask:0xf bank_mask:0xf bound_ctrl:1
	v_and_b32_e32 v47, 0xffff0000, v190
	v_readlane_b32 s0, v38, 0
	v_readlane_b32 s3, v38, 16
	v_readlane_b32 s2, v38, 32
	v_readlane_b32 s16, v38, 48
	v_add_f32_e32 v38, v112, v113
	v_mov_b32_e32 v64, s3
	v_mov_b32_e32 v112, s16
	v_add_f32_dpp v38, v38, v38 quad_perm:[1,0,3,2] row_mask:0xf bank_mask:0xf bound_ctrl:1
	v_and_b32_e32 v46, 0xffff0000, v188
	v_mov_b32_e32 v50, v49
	v_add_f32_dpp v38, v38, v38 quad_perm:[2,3,0,1] row_mask:0xf bank_mask:0xf bound_ctrl:1
	v_and_b32_e32 v45, 0xffff0000, v189
	v_mov_b32_e32 v51, v43
	v_add_f32_dpp v38, v38, v38 row_half_mirror row_mask:0xf bank_mask:0xf bound_ctrl:1
	v_lshlrev_b32_e32 v36, 16, v187
	v_lshlrev_b32_e32 v40, 16, v188
	v_add_f32_dpp v38, v38, v38 row_mirror row_mask:0xf bank_mask:0xf bound_ctrl:1
	v_lshlrev_b32_e32 v41, 16, v189
	v_readlane_b32 s17, v38, 16
	v_readlane_b32 s1, v38, 0
	v_readlane_b32 s3, v38, 32
	v_mov_b32_e32 v65, s17
	v_pk_add_f32 v[64:65], s[0:1], v[64:65]
	v_readlane_b32 s0, v38, 48
	s_nop 1
	v_mov_b32_e32 v113, s0
	v_pk_add_f32 v[112:113], s[2:3], v[112:113]
	s_nop 0
; #define LAS __attribute__((address_space(3)))
; DI unsigned pk2(float lo, float hi) { return f2bf(lo) | (f2bf(hi) << 16); }
; DI float bflo(unsigned w) { return __uint_as_float(w << 16); }
; DI float bfhi(unsigned w) { return __uint_as_float(w & 0xffff0000u); }
; DI float siluf_(float x) { return x * __builtin_amdgcn_rcpf(1.0f + __expf(-x)); }
; DI float wave_sum(float v) { v = row16_sum(v); return (rdlane(v, 0) + rdlane(v, 16)) + (rdlane(v, 32) + rdlane(v, 48)); }
; DI void gdn_unit(const Params& P, bf16_t* proj, const float* gb, int b, int h, LAS unsigned char* lds) {
;     ...
;             for (int i = 0; i < 8; ++i) {
;                 float a0 = 0.f, a1 = 0.f;
; #pragma unroll
;                 for (int j = 0; j < 4; ++j) { a0 += cw[j][0] * bflo(raw[i + j]); a1 += cw[j][1] * bfhi(raw[i + j]); }
;                 a0 = siluf_(a0); a1 = siluf_(a1);
;                 if (w < 2) {
;                     const float ss = wave_sum(a0 * a0 + a1 * a1);
;                     const float rs = rsqrtf(ss + 1e-6f) * (w == 0 ? 0.08838834764831845f : 1.0f);
;                     a0 *= rs; a1 *= rs;
;                 }
;                 o0[i] = a0; o1[i] = a1;
;             }
;             if (w < 2) {
;                 const int off = (w == 0) ? Q_OFF : K_OFF;
; #pragma unroll
;                 for (int i = 0; i < 8; ++i) *(LAS unsigned*)(lds + off + (wave * 8 + i) * 272 + lane * 4) = pk2(o0[i], o1[i]);
	v_pk_add_f32 v[64:65], v[64:65], v[112:113]
	s_nop 0
	v_pk_add_f32 v[64:65], v[64:65], s[76:77] op_sel_hi:[1,0]
	s_nop 0
	s_nop 0
	s_nop 0
	s_nop 0
	s_nop 0
	s_nop 0
	v_rsq_f32_e32 v64, v64
	s_nop 0
	s_nop 0
	v_rsq_f32_e32 v65, v65
	v_add_f32_e32 v38, v60, v61
	s_nop 0
	s_nop 0
	v_add_f32_dpp v38, v38, v38 quad_perm:[1,0,3,2] row_mask:0xf bank_mask:0xf bound_ctrl:1
	s_nop 0
	s_nop 0
	v_add_f32_dpp v38, v38, v38 quad_perm:[2,3,0,1] row_mask:0xf bank_mask:0xf bound_ctrl:1
	v_pk_mul_f32 v[32:33], v[32:33], v[64:65]
	s_nop 0
	v_add_f32_dpp v38, v38, v38 row_half_mirror row_mask:0xf bank_mask:0xf bound_ctrl:1
	v_and_b32_sdwa v57, v32, v166 dst_sel:DWORD dst_unused:UNUSED_PAD src0_sel:WORD_1 src1_sel:DWORD
	v_add3_u32 v32, v32, v57, s68
	v_add_f32_dpp v38, v38, v38 row_mirror row_mask:0xf bank_mask:0xf bound_ctrl:1
	s_nop 0
	v_readlane_b32 s0, v38, 0
	v_readlane_b32 s3, v38, 16
	v_readlane_b32 s2, v38, 32
	v_readlane_b32 s16, v38, 48
	v_add_f32_e32 v38, v110, v111
	v_mov_b32_e32 v60, s3
	v_mov_b32_e32 v110, s16
	v_add_f32_dpp v38, v38, v38 quad_perm:[1,0,3,2] row_mask:0xf bank_mask:0xf bound_ctrl:1
	s_nop 1
	v_add_f32_dpp v38, v38, v38 quad_perm:[2,3,0,1] row_mask:0xf bank_mask:0xf bound_ctrl:1
	s_nop 1
	v_add_f32_dpp v38, v38, v38 row_half_mirror row_mask:0xf bank_mask:0xf bound_ctrl:1
	s_nop 1
	v_add_f32_dpp v38, v38, v38 row_mirror row_mask:0xf bank_mask:0xf bound_ctrl:1
	s_nop 0
	v_readlane_b32 s17, v38, 16
	v_readlane_b32 s1, v38, 0
	v_readlane_b32 s3, v38, 32
	v_mov_b32_e32 v61, s17
	v_pk_add_f32 v[60:61], s[0:1], v[60:61]
	v_readlane_b32 s0, v38, 48
	s_nop 1
	v_mov_b32_e32 v111, s0
	v_pk_add_f32 v[110:111], s[2:3], v[110:111]
	s_nop 0
	v_pk_add_f32 v[60:61], v[60:61], v[110:111]
	s_nop 0
	v_pk_add_f32 v[60:61], v[60:61], s[76:77] op_sel_hi:[1,0]
	s_nop 0
	s_nop 0
	s_nop 0
	s_nop 0
	s_nop 0
	s_nop 0
	v_rsq_f32_e32 v60, v60
	s_nop 0
	s_nop 0
	v_rsq_f32_e32 v61, v61
	s_nop 0
	v_cvt_pk_bf16_f32 v33, v33, v33
	v_and_b32_e32 v33, 0xffff0000, v33
	s_nop 0
	s_nop 0
	s_nop 0
	s_nop 0
	v_mov_b32_e32 v111, v61
	v_pk_mul_f32 v[52:53], v[52:53], v[60:61]
	v_mov_b32_e32 v61, v65
	v_mov_b32_e32 v110, v64
	v_pk_mul_f32 v[58:59], v[58:59], v[60:61]
	v_pk_mul_f32 v[62:63], v[62:63], v[110:111]
	v_and_b32_sdwa v61, v59, v166 dst_sel:DWORD dst_unused:UNUSED_PAD src0_sel:WORD_1 src1_sel:DWORD
	v_add3_u32 v61, v59, v61, s68
	v_cvt_pk_bf16_f32 v57, v62, v62
	v_and_b32_sdwa v62, v58, v166 dst_sel:DWORD dst_unused:UNUSED_PAD src0_sel:WORD_1 src1_sel:DWORD
	v_cvt_pk_bf16_f32 v52, v52, v52
	v_cvt_pk_bf16_f32 v38, v63, v63
	v_lshrrev_b32_e32 v57, 16, v57
	v_add3_u32 v62, v58, v62, s68
	v_and_b32_sdwa v58, v53, v166 dst_sel:DWORD dst_unused:UNUSED_PAD src0_sel:WORD_1 src1_sel:DWORD
	v_and_b32_e32 v52, 0xffff0000, v52
	v_lshrrev_b32_e32 v60, 16, v38
	v_and_or_b32 v38, v32, s39, v57
	v_add3_u32 v53, v53, v58, s68
	v_or_b32_sdwa v58, v52, v62 dst_sel:DWORD dst_unused:UNUSED_PAD src0_sel:DWORD src1_sel:WORD_1
	v_add_u32_e32 v59, 0x4400, v56
	ds_write2_b32 v59, v38, v58 offset1:68
	v_and_or_b32 v38, v53, s39, v60
	v_or_b32_sdwa v58, v33, v61 dst_sel:DWORD dst_unused:UNUSED_PAD src0_sel:DWORD src1_sel:WORD_1
	ds_write2_b32 v59, v38, v58 offset0:136 offset1:204
	v_mov_b32_e32 v58, v48
	v_mov_b32_e32 v59, v44
	v_pk_fma_f32 v[58:59], v[76:77], v[58:59], 0 op_sel_hi:[1,1,0]
	v_pk_mov_b32 v[48:49], v[48:49], v[46:47] op_sel:[1,0]
	v_or_b32_sdwa v32, v32, v52 dst_sel:DWORD dst_unused:UNUSED_PAD src0_sel:WORD_1 src1_sel:DWORD
	v_pk_fma_f32 v[48:49], v[92:93], v[48:49], v[58:59]
	v_mov_b32_e32 v58, v43
	v_mov_b32_e32 v59, v47
	v_pk_fma_f32 v[48:49], v[94:95], v[58:59], v[48:49]
	v_mov_b32_e32 v52, v44
	v_pk_fma_f32 v[48:49], v[96:97], v[44:45], v[48:49]
	v_pk_mov_b32 v[42:43], v[42:43], v[44:45] op_sel:[1,0]
	v_mul_f32_e32 v38, 0xbfb8aa3b, v49
	v_exp_f32_e32 v38, v38
	v_pk_fma_f32 v[44:45], v[76:77], v[50:51], 0 op_sel_hi:[1,1,0]
	v_or_b32_sdwa v33, v33, v53 dst_sel:DWORD dst_unused:UNUSED_PAD src0_sel:DWORD src1_sel:WORD_1
	v_mov_b32_e32 v53, v46
	v_add_f32_e32 v38, 1.0, v38
	v_rcp_f32_e32 v59, v38
	v_mul_f32_e32 v38, 0xbfb8aa3b, v48
	v_exp_f32_e32 v38, v38
	v_pk_fma_f32 v[42:43], v[92:93], v[42:43], v[44:45]
	v_lshlrev_b32_e32 v50, 16, v195
	v_pk_fma_f32 v[42:43], v[94:95], v[52:53], v[42:43]
	v_add_f32_e32 v38, 1.0, v38
	v_pk_fma_f32 v[42:43], v[96:97], v[46:47], v[42:43]
	v_rcp_f32_e32 v58, v38
	v_mul_f32_e32 v38, 0xbfb8aa3b, v42
	v_exp_f32_e32 v38, v38
	v_pk_mov_b32 v[46:47], v[34:35], v[40:41] op_sel:[1,0]
	v_pk_fma_f32 v[34:35], v[98:99], v[34:35], 0 op_sel_hi:[1,1,0]
	v_pk_mul_f32 v[48:49], v[48:49], v[58:59]
	v_add_f32_e32 v38, 1.0, v38
	v_rcp_f32_e32 v44, v38
	v_mul_f32_e32 v38, 0xbfb8aa3b, v43
	v_exp_f32_e32 v38, v38
	v_lshlrev_b32_e32 v51, 16, v197
	v_lshlrev_b32_e32 v53, 16, v196
	v_add_f32_e32 v38, 1.0, v38
	v_rcp_f32_e32 v45, v38
	v_pk_mov_b32 v[38:39], v[38:39], v[36:37] op_sel:[1,0]
	v_pk_mul_f32 v[42:43], v[42:43], v[44:45]
	v_pk_fma_f32 v[44:45], v[98:99], v[38:39], 0 op_sel_hi:[1,1,0]
	v_pk_fma_f32 v[34:35], v[78:79], v[38:39], v[34:35]
	v_pk_fma_f32 v[44:45], v[78:79], v[46:47], v[44:45]
	v_pk_fma_f32 v[34:35], v[80:81], v[46:47], v[34:35]
	v_pk_fma_f32 v[44:45], v[80:81], v[36:37], v[44:45]
	v_pk_fma_f32 v[34:35], v[82:83], v[36:37], v[34:35]
	v_pk_fma_f32 v[40:41], v[82:83], v[40:41], v[44:45]
	v_mul_f32_e32 v36, 0xbfb8aa3b, v34
	v_mul_f32_e32 v44, 0xbfb8aa3b, v41
	v_exp_f32_e32 v44, v44
	v_mul_f32_e32 v37, 0xbfb8aa3b, v35
	v_exp_f32_e32 v36, v36
	v_exp_f32_e32 v37, v37
	v_add_f32_e32 v44, 1.0, v44
	v_rcp_f32_e32 v45, v44
	v_mul_f32_e32 v44, 0xbfb8aa3b, v40
	v_exp_f32_e32 v44, v44
	v_add_f32_e32 v36, 1.0, v36
	v_add_f32_e32 v37, 1.0, v37
	v_rcp_f32_e32 v36, v36
; #define LAS __attribute__((address_space(3)))
; DI unsigned pk2(float lo, float hi) { return f2bf(lo) | (f2bf(hi) << 16); }
; DI float bflo(unsigned w) { return __uint_as_float(w << 16); }
; DI float bfhi(unsigned w) { return __uint_as_float(w & 0xffff0000u); }
; DI float siluf_(float x) { return x * __builtin_amdgcn_rcpf(1.0f + __expf(-x)); }
; DI float wave_sum(float v) { v = row16_sum(v); return (rdlane(v, 0) + rdlane(v, 16)) + (rdlane(v, 32) + rdlane(v, 48)); }
; DI void gdn_unit(const Params& P, bf16_t* proj, const float* gb, int b, int h, LAS unsigned char* lds) {
;     ...
;                 for (int j = 0; j < 4; ++j) { a0 += cw[j][0] * bflo(raw[i + j]); a1 += cw[j][1] * bfhi(raw[i + j]); }
;                 a0 = siluf_(a0); a1 = siluf_(a1);
;                 if (w < 2) {
;                     const float ss = wave_sum(a0 * a0 + a1 * a1);
;                     const float rs = rsqrtf(ss + 1e-6f) * (w == 0 ? 0.08838834764831845f : 1.0f);
;                     a0 *= rs; a1 *= rs;
;                 }
;                 o0[i] = a0; o1[i] = a1;
;             }
;             if (w < 2) {
;                 const int off = (w == 0) ? Q_OFF : K_OFF;
; #pragma unroll
;                 for (int i = 0; i < 8; ++i) *(LAS unsigned*)(lds + off + (wave * 8 + i) * 272 + lane * 4) = pk2(o0[i], o1[i]);
;             }
;             if (w >= 1) {
;                 const int off = (w == 1) ? KT_OFF : VT_OFF;
;                 u32x4 w0, w1;
;                 w0.x = pk2(o0[0], o0[1]); w0.y = pk2(o0[2], o0[3]); w0.z = pk2(o0[4], o0[5]); w0.w = pk2(o0[6], o0[7]);
;                 w1.x = pk2(o1[0], o1[1]); w1.y = pk2(o1[2], o1[3]); w1.z = pk2(o1[4], o1[5]); w1.w = pk2(o1[6], o1[7]);
;                 *(LAS u32x4*)(lds + off + (2 * lane) * 144 + wave * 16) = w0;
;                 *(LAS u32x4*)(lds + off + (2 * lane + 1) * 144 + wave * 16) = w1;
	v_add_f32_e32 v44, 1.0, v44
	v_rcp_f32_e32 v44, v44
	v_rcp_f32_e32 v37, v37
	v_mov_b32_e32 v38, v42
	v_mov_b32_e32 v46, v43
	v_pk_mul_f32 v[40:41], v[40:41], v[44:45]
	v_mov_b32_e32 v44, v49
	v_mov_b32_e32 v45, v41
	v_pk_mul_f32 v[34:35], v[34:35], v[36:37]
	v_pk_mul_f32 v[44:45], v[44:45], v[44:45]
	v_mov_b32_e32 v36, v48
	v_mov_b32_e32 v37, v34
	v_pk_mul_f32 v[36:37], v[36:37], v[36:37]
	v_add_f32_e32 v44, v44, v45
	v_add_f32_e32 v36, v36, v37
	v_mov_b32_e32 v39, v40
	v_add_f32_dpp v44, v44, v44 quad_perm:[1,0,3,2] row_mask:0xf bank_mask:0xf bound_ctrl:1
	v_add_f32_dpp v36, v36, v36 quad_perm:[1,0,3,2] row_mask:0xf bank_mask:0xf bound_ctrl:1
	v_pk_mul_f32 v[38:39], v[38:39], v[38:39]
	v_add_f32_dpp v44, v44, v44 quad_perm:[2,3,0,1] row_mask:0xf bank_mask:0xf bound_ctrl:1
	v_add_f32_dpp v36, v36, v36 quad_perm:[2,3,0,1] row_mask:0xf bank_mask:0xf bound_ctrl:1
	v_add_f32_e32 v38, v38, v39
	v_add_f32_dpp v44, v44, v44 row_half_mirror row_mask:0xf bank_mask:0xf bound_ctrl:1
	v_add_f32_dpp v36, v36, v36 row_half_mirror row_mask:0xf bank_mask:0xf bound_ctrl:1
	v_add_f32_dpp v38, v38, v38 quad_perm:[1,0,3,2] row_mask:0xf bank_mask:0xf bound_ctrl:1
	v_add_f32_dpp v44, v44, v44 row_mirror row_mask:0xf bank_mask:0xf bound_ctrl:1
	v_mov_b32_e32 v47, v35
	v_readlane_b32 s1, v44, 0
	v_readlane_b32 s2, v44, 16
	v_readlane_b32 s3, v44, 32
	v_readlane_b32 s16, v44, 48
	v_add_f32_dpp v44, v36, v36 row_mirror row_mask:0xf bank_mask:0xf bound_ctrl:1
	v_mov_b32_e32 v37, s2
	v_readlane_b32 s17, v44, 16
	v_readlane_b32 s0, v44, 0
	v_readlane_b32 s2, v44, 32
	v_mov_b32_e32 v36, s17
	v_pk_add_f32 v[36:37], s[0:1], v[36:37]
	v_readlane_b32 s0, v44, 48
	v_mov_b32_e32 v45, s16
	v_add_f32_dpp v38, v38, v38 quad_perm:[2,3,0,1] row_mask:0xf bank_mask:0xf bound_ctrl:1
	v_mov_b32_e32 v44, s0
	v_pk_add_f32 v[44:45], s[2:3], v[44:45]
	v_add_f32_dpp v38, v38, v38 row_half_mirror row_mask:0xf bank_mask:0xf bound_ctrl:1
	v_pk_add_f32 v[36:37], v[36:37], v[44:45]
	v_pk_mul_f32 v[46:47], v[46:47], v[46:47]
	v_pk_add_f32 v[36:37], v[36:37], s[76:77] op_sel_hi:[1,0]
	v_add_f32_dpp v38, v38, v38 row_mirror row_mask:0xf bank_mask:0xf bound_ctrl:1
	s_nop 0
	s_nop 0
	s_nop 0
	v_readlane_b32 s3, v38, 16
	s_nop 0
	s_nop 0
	s_nop 0
	v_rsq_f32_e32 v37, v37
	v_rsq_f32_e32 v36, v36
	v_readlane_b32 s2, v38, 32
	v_readlane_b32 s16, v38, 48
	s_nop 0
	s_nop 0
	s_nop 0
	v_readlane_b32 s0, v38, 0
	v_add_f32_e32 v38, v46, v47
	s_nop 0
	v_mov_b32_e32 v47, v50
	v_add_f32_dpp v38, v38, v38 quad_perm:[1,0,3,2] row_mask:0xf bank_mask:0xf bound_ctrl:1
	s_nop 1
	v_add_f32_dpp v38, v38, v38 quad_perm:[2,3,0,1] row_mask:0xf bank_mask:0xf bound_ctrl:1
	s_nop 1
	v_add_f32_dpp v38, v38, v38 row_half_mirror row_mask:0xf bank_mask:0xf bound_ctrl:1
	s_nop 1
	v_add_f32_dpp v44, v38, v38 row_mirror row_mask:0xf bank_mask:0xf bound_ctrl:1
	v_mov_b32_e32 v38, s3
	v_readlane_b32 s17, v44, 16
	v_readlane_b32 s1, v44, 0
	v_readlane_b32 s3, v44, 32
	v_mov_b32_e32 v39, s17
	v_pk_add_f32 v[38:39], s[0:1], v[38:39]
	v_readlane_b32 s0, v44, 48
	v_mov_b32_e32 v44, s16
	s_nop 0
	v_mov_b32_e32 v45, s0
	v_pk_add_f32 v[44:45], s[2:3], v[44:45]
	s_nop 0
	v_pk_add_f32 v[38:39], v[38:39], v[44:45]
	s_nop 0
	v_pk_add_f32 v[38:39], v[38:39], s[76:77] op_sel_hi:[1,0]
	s_nop 0
	s_nop 0
	s_nop 0
	s_nop 0
	s_nop 0
	s_nop 0
	s_nop 0
	s_nop 0
	v_rsq_f32_e32 v38, v38
	v_rsq_f32_e32 v39, v39
	s_nop 0
	s_nop 0
	s_nop 0
	s_nop 0
	s_nop 0
	v_mov_b32_e32 v44, v38
	v_mov_b32_e32 v45, v37
	v_pk_mul_f32 v[40:41], v[40:41], v[44:45]
	s_nop 0
	v_and_b32_sdwa v44, v41, v166 dst_sel:DWORD dst_unused:UNUSED_PAD src0_sel:WORD_1 src1_sel:DWORD
	v_and_b32_sdwa v45, v40, v166 dst_sel:DWORD dst_unused:UNUSED_PAD src0_sel:WORD_1 src1_sel:DWORD
	v_add3_u32 v45, v40, v45, s68
	v_add3_u32 v44, v41, v44, s68
	v_pk_mul_f32 v[40:41], v[48:49], v[36:37]
	v_lshlrev_b32_e32 v48, 16, v193
	v_cvt_pk_bf16_f32 v37, v41, v41
	v_and_b32_e32 v41, 0xffff0000, v37
	v_mov_b32_e32 v37, v39
	v_pk_mul_f32 v[34:35], v[34:35], v[36:37]
	v_pk_mul_f32 v[36:37], v[42:43], v[38:39]
	v_and_b32_sdwa v46, v40, v166 dst_sel:DWORD dst_unused:UNUSED_PAD src0_sel:WORD_1 src1_sel:DWORD
	v_cvt_pk_bf16_f32 v34, v34, v34
	v_cvt_pk_bf16_f32 v36, v36, v36
	v_add3_u32 v40, v40, v46, s68
	v_cvt_pk_bf16_f32 v35, v35, v35
	v_lshrrev_b32_e32 v34, 16, v34
	v_and_b32_sdwa v39, v37, v166 dst_sel:DWORD dst_unused:UNUSED_PAD src0_sel:WORD_1 src1_sel:DWORD
	v_and_b32_e32 v42, 0xffff0000, v36
	v_lshrrev_b32_e32 v35, 16, v35
	v_and_or_b32 v38, v40, s39, v34
	v_add3_u32 v43, v37, v39, s68
	v_or_b32_sdwa v36, v42, v45 dst_sel:DWORD dst_unused:UNUSED_PAD src0_sel:DWORD src1_sel:WORD_1
	v_add_u32_e32 v37, 0x4800, v56
	v_or_b32_sdwa v46, v41, v44 dst_sel:DWORD dst_unused:UNUSED_PAD src0_sel:DWORD src1_sel:WORD_1
	ds_write2_b32 v37, v38, v36 offset0:16 offset1:84
	v_and_or_b32 v36, v43, s39, v35
	ds_write2_b32 v37, v36, v46 offset0:152 offset1:220
	v_lshlrev_b32_e32 v46, 16, v191
	v_lshlrev_b32_e32 v49, 16, v194
	v_pk_fma_f32 v[46:47], v[84:85], v[46:47], 0 op_sel_hi:[1,1,0]
	v_mov_b32_e32 v52, v49
	v_pk_fma_f32 v[46:47], v[86:87], v[48:49], v[46:47]
	v_and_or_b32 v39, v44, s39, v35
	v_pk_fma_f32 v[46:47], v[88:89], v[50:51], v[46:47]
	v_or_b32_sdwa v35, v41, v43 dst_sel:DWORD dst_unused:UNUSED_PAD src0_sel:DWORD src1_sel:WORD_1
	v_pk_fma_f32 v[46:47], v[90:91], v[52:53], v[46:47]
	v_pk_fma_f32 v[48:49], v[84:85], v[48:49], 0 op_sel_hi:[1,1,0]
	v_mul_f32_e32 v41, 0xbfb8aa3b, v46
	v_exp_f32_e32 v41, v41
	v_pk_fma_f32 v[48:49], v[86:87], v[50:51], v[48:49]
	v_and_or_b32 v36, v62, s39, v57
	v_lshlrev_b32_e32 v57, 16, v198
	v_mov_b32_e32 v56, v51
	v_pk_fma_f32 v[48:49], v[88:89], v[52:53], v[48:49]
; #define LAS __attribute__((address_space(3)))
; DI unsigned pk2(float lo, float hi) { return f2bf(lo) | (f2bf(hi) << 16); }
; DI float bflo(unsigned w) { return __uint_as_float(w << 16); }
; DI float bfhi(unsigned w) { return __uint_as_float(w & 0xffff0000u); }
; DI float siluf_(float x) { return x * __builtin_amdgcn_rcpf(1.0f + __expf(-x)); }
; DI float wave_sum(float v) { v = row16_sum(v); return (rdlane(v, 0) + rdlane(v, 16)) + (rdlane(v, 32) + rdlane(v, 48)); }
; DI void gdn_unit(const Params& P, bf16_t* proj, const float* gb, int b, int h, LAS unsigned char* lds) {
;     ...
;         for (int w = 0; w < 3; ++w) {
;             const f32x2 (&cw)[4] = cwr[w];
;             const unsigned (&raw)[11] = rawq[w];
;             float o0[8], o1[8];
; #pragma unroll
;             for (int i = 0; i < 8; ++i) {
;                 float a0 = 0.f, a1 = 0.f;
; #pragma unroll
;                 for (int j = 0; j < 4; ++j) { a0 += cw[j][0] * bflo(raw[i + j]); a1 += cw[j][1] * bfhi(raw[i + j]); }
;                 a0 = siluf_(a0); a1 = siluf_(a1);
;                 if (w < 2) {
;                     const float ss = wave_sum(a0 * a0 + a1 * a1);
;                     const float rs = rsqrtf(ss + 1e-6f) * (w == 0 ? 0.08838834764831845f : 1.0f);
;                     a0 *= rs; a1 *= rs;
;                 }
;                 o0[i] = a0; o1[i] = a1;
;             }
;             if (w < 2) {
;                 const int off = (w == 0) ? Q_OFF : K_OFF;
; #pragma unroll
;                 for (int i = 0; i < 8; ++i) *(LAS unsigned*)(lds + off + (wave * 8 + i) * 272 + lane * 4) = pk2(o0[i], o1[i]);
;             }
;             if (w >= 1) {
;                 const int off = (w == 1) ? KT_OFF : VT_OFF;
;                 u32x4 w0, w1;
;                 w0.x = pk2(o0[0], o0[1]); w0.y = pk2(o0[2], o0[3]); w0.z = pk2(o0[4], o0[5]); w0.w = pk2(o0[6], o0[7]);
;                 w1.x = pk2(o1[0], o1[1]); w1.y = pk2(o1[2], o1[3]); w1.z = pk2(o1[4], o1[5]); w1.w = pk2(o1[6], o1[7]);
;                 *(LAS u32x4*)(lds + off + (2 * lane) * 144 + wave * 16) = w0;
;                 *(LAS u32x4*)(lds + off + (2 * lane + 1) * 144 + wave * 16) = w1;
;             }
;         }
;         if (n + 1 < 32) {
	v_add_f32_e32 v41, 1.0, v41
	v_pk_fma_f32 v[48:49], v[90:91], v[56:57], v[48:49]
	v_rcp_f32_e32 v58, v41
	v_mul_f32_e32 v41, 0xbfb8aa3b, v48
	v_exp_f32_e32 v41, v41
	v_add3_u32 v62, v54, v55, s4
	v_lshlrev_b32_e32 v54, 16, v199
	v_lshlrev_b32_e32 v55, 16, v200
	v_add_f32_e32 v41, 1.0, v41
	v_rcp_f32_e32 v50, v41
	v_mul_f32_e32 v41, 0xbfb8aa3b, v47
	v_exp_f32_e32 v41, v41
	v_pk_mov_b32 v[52:53], v[52:53], v[54:55] op_sel:[1,0]
	v_and_or_b32 v37, v61, s39, v60
	v_and_or_b32 v38, v45, s39, v34
	v_add_f32_e32 v41, 1.0, v41
	v_rcp_f32_e32 v59, v41
	v_mul_f32_e32 v41, 0xbfb8aa3b, v49
	v_exp_f32_e32 v41, v41
	v_or_b32_sdwa v34, v40, v42 dst_sel:DWORD dst_unused:UNUSED_PAD src0_sel:WORD_1 src1_sel:DWORD
	v_pk_mul_f32 v[46:47], v[46:47], v[58:59]
	v_pk_fma_f32 v[58:59], v[84:85], v[52:53], 0 op_sel_hi:[1,1,0]
	v_add_f32_e32 v41, 1.0, v41
	v_rcp_f32_e32 v51, v41
	v_and_b32_e32 v42, 0xffff0000, v195
	ds_write_b128 v62, v[36:39] offset:34816
	ds_write_b128 v62, v[32:35] offset:34960
	v_and_b32_e32 v44, 0xffff0000, v191
	v_pk_mul_f32 v[48:49], v[48:49], v[50:51]
	v_lshlrev_b32_e32 v50, 16, v201
	v_lshlrev_b32_e32 v51, 16, v202
	v_pk_mov_b32 v[60:61], v[56:57], v[50:51] op_sel:[1,0]
	v_pk_fma_f32 v[56:57], v[84:85], v[56:57], 0 op_sel_hi:[1,1,0]
	v_pk_fma_f32 v[58:59], v[86:87], v[60:61], v[58:59]
	v_pk_fma_f32 v[52:53], v[86:87], v[52:53], v[56:57]
	v_pk_fma_f32 v[58:59], v[88:89], v[54:55], v[58:59]
	v_pk_fma_f32 v[52:53], v[88:89], v[60:61], v[52:53]
	v_pk_fma_f32 v[50:51], v[90:91], v[50:51], v[58:59]
	v_pk_fma_f32 v[52:53], v[90:91], v[54:55], v[52:53]
	v_mul_f32_e32 v41, 0xbfb8aa3b, v51
	v_exp_f32_e32 v41, v41
	s_nop 0
	s_nop 0
	s_nop 0
	v_add_f32_e32 v41, 1.0, v41
	v_rcp_f32_e32 v59, v41
	v_mul_f32_e32 v41, 0xbfb8aa3b, v52
	v_exp_f32_e32 v41, v41
	s_nop 0
	s_nop 0
	v_and_b32_e32 v36, 0xffff0000, v194
	v_add_f32_e32 v41, 1.0, v41
	v_rcp_f32_e32 v54, v41
	v_mul_f32_e32 v41, 0xbfb8aa3b, v50
	v_exp_f32_e32 v41, v41
	v_cvt_pk_bf16_f32 v47, v47, v49
	v_mov_b32_e32 v45, v42
	v_and_b32_e32 v40, 0xffff0000, v193
	v_add_f32_e32 v41, 1.0, v41
	v_rcp_f32_e32 v58, v41
	v_mul_f32_e32 v41, 0xbfb8aa3b, v53
	v_exp_f32_e32 v41, v41
	v_and_b32_e32 v32, 0xffff0000, v197
	v_pk_mul_f32 v[50:51], v[50:51], v[58:59]
	v_pk_fma_f32 v[44:45], v[100:101], v[44:45], 0 op_sel_hi:[1,1,0]
	v_add_f32_e32 v41, 1.0, v41
	v_rcp_f32_e32 v55, v41
	s_nop 0
	s_nop 0
	s_nop 0
	v_pk_mul_f32 v[52:53], v[52:53], v[54:55]
	v_cvt_pk_bf16_f32 v54, v48, v48
	v_bfe_u32 v48, v46, 16, 1
	v_add3_u32 v46, v46, v48, s68
	v_cvt_pk_bf16_f32 v49, v53, v51
	v_mov_b32_e32 v41, v36
	v_cvt_pk_bf16_f32 v48, v52, v50
	v_mov_b32_e32 v43, v32
	v_pk_fma_f32 v[44:45], v[102:103], v[40:41], v[44:45]
	v_and_b32_e32 v37, 0xffff0000, v196
	v_pk_fma_f32 v[44:45], v[104:105], v[42:43], v[44:45]
	v_pk_fma_f32 v[40:41], v[100:101], v[40:41], 0 op_sel_hi:[1,1,0]
	v_pk_fma_f32 v[44:45], v[106:107], v[36:37], v[44:45]
	v_pk_fma_f32 v[40:41], v[102:103], v[42:43], v[40:41]
	v_mul_f32_e32 v43, 0xbfb8aa3b, v45
	v_exp_f32_e32 v43, v43
	v_and_b32_e32 v33, 0xffff0000, v198
	v_pk_fma_f32 v[40:41], v[104:105], v[36:37], v[40:41]
	v_mul_f32_e32 v50, 0xbfb8aa3b, v44
	v_pk_fma_f32 v[40:41], v[106:107], v[32:33], v[40:41]
	v_add_f32_e32 v43, 1.0, v43
	v_mul_f32_e32 v42, 0xbfb8aa3b, v40
	v_rcp_f32_e32 v51, v43
	v_mul_f32_e32 v43, 0xbfb8aa3b, v41
	v_exp_f32_e32 v50, v50
	v_exp_f32_e32 v42, v42
	v_exp_f32_e32 v43, v43
	v_and_b32_e32 v35, 0xffff0000, v200
	v_add_f32_e32 v50, 1.0, v50
	v_add_f32_e32 v42, 1.0, v42
	v_add_f32_e32 v43, 1.0, v43
	v_rcp_f32_e32 v50, v50
	v_rcp_f32_e32 v42, v42
	v_rcp_f32_e32 v43, v43
	v_and_b32_e32 v34, 0xffff0000, v199
	v_and_b32_e32 v39, 0xffff0000, v202
	v_and_b32_e32 v38, 0xffff0000, v201
	v_pk_mov_b32 v[36:37], v[36:37], v[34:35] op_sel:[1,0]
	v_pk_mul_f32 v[44:45], v[44:45], v[50:51]
	v_pk_mul_f32 v[40:41], v[40:41], v[42:43]
	v_pk_fma_f32 v[42:43], v[100:101], v[36:37], 0 op_sel_hi:[1,1,0]
	v_pk_mov_b32 v[50:51], v[32:33], v[38:39] op_sel:[1,0]
	v_pk_fma_f32 v[32:33], v[100:101], v[32:33], 0 op_sel_hi:[1,1,0]
	v_pk_fma_f32 v[42:43], v[102:103], v[50:51], v[42:43]
	v_pk_fma_f32 v[32:33], v[102:103], v[36:37], v[32:33]
	v_pk_fma_f32 v[42:43], v[104:105], v[34:35], v[42:43]
	v_pk_fma_f32 v[32:33], v[104:105], v[50:51], v[32:33]
	v_pk_fma_f32 v[38:39], v[106:107], v[38:39], v[42:43]
	v_pk_fma_f32 v[32:33], v[106:107], v[34:35], v[32:33]
	v_mul_f32_e32 v42, 0xbfb8aa3b, v39
	v_mul_f32_e32 v35, 0xbfb8aa3b, v38
	v_exp_f32_e32 v42, v42
	v_exp_f32_e32 v35, v35
	v_mul_f32_e32 v34, 0xbfb8aa3b, v32
	v_exp_f32_e32 v34, v34
	v_add_f32_e32 v42, 1.0, v42
	v_add_f32_e32 v35, 1.0, v35
	v_rcp_f32_e32 v43, v42
	v_rcp_f32_e32 v42, v35
	v_mul_f32_e32 v35, 0xbfb8aa3b, v33
	v_exp_f32_e32 v35, v35
	v_add_f32_e32 v34, 1.0, v34
	v_rcp_f32_e32 v34, v34
	v_pk_mul_f32 v[36:37], v[38:39], v[42:43]
	v_add_f32_e32 v35, 1.0, v35
	v_rcp_f32_e32 v35, v35
	s_nop 0
	s_nop 0
	v_cvt_pk_bf16_f32 v38, v41, v41
	v_pk_mul_f32 v[32:33], v[32:33], v[34:35]
	v_bfe_u32 v35, v36, 16, 1
	v_add3_u32 v36, v36, v35, s68
	v_cvt_pk_bf16_f32 v34, v37, v37
	v_cvt_pk_bf16_f32 v37, v40, v40
	v_bfe_u32 v41, v45, 16, 1
	v_lshrrev_b32_e32 v46, 16, v46
	v_cvt_pk_bf16_f32 v33, v33, v33
	v_cvt_pk_bf16_f32 v32, v32, v32
	v_add3_u32 v35, v45, v41, s68
	v_cvt_pk_bf16_f32 v39, v44, v44
	v_and_or_b32 v46, v54, s39, v46
	v_lshrrev_b32_e32 v32, 16, v32
	v_lshrrev_b32_e32 v33, 16, v33
	v_lshrrev_b32_e32 v39, 16, v39
	v_lshrrev_b32_e32 v40, 16, v35
	v_lshlrev_b32_e32 v60, 1, v67
	v_and_or_b32 v35, v34, s39, v33
	v_and_or_b32 v34, v36, s39, v32
	v_and_or_b32 v33, v38, s39, v40
	v_and_or_b32 v32, v37, s39, v39
	ds_write_b128 v62, v[46:49] offset:53248
	ds_write_b128 v62, v[32:35] offset:53392
	s_cbranch_scc1 .LBB0_425
; DI void gdn_unit(const Params& P, bf16_t* proj, const float* gb, int b, int h, LAS unsigned char* lds) {
;     ...
;         if (n + 1 < 32) {
; #pragma unroll
;             for (int w = 0; w < 3; ++w) {
;                 const bf16_t* rbase = proj + (size_t)(t0 + 64 + wave * 8 - 3) * PJ1 + w * 1024 + h * 128;
; #pragma unroll
;                 for (int i = 0; i < 11; ++i) rawq[w][i] = *(const unsigned*)(rbase + i * PJ1 + 2 * lane);
;             }
;             gbl = gb[(size_t)(t0 + 64 + lane) * 16 + h]; gai = gb[(size_t)(t0 + 64 + lane) * 16 + 8 + h];
	s_add_i32 s0, s41, s42
	s_add_i32 s0, s0, -3
	s_ashr_i32 s1, s0, 31
	s_lshl_b64 s[0:1], s[0:1], 13
	s_add_u32 s0, s43, s0
	s_addc_u32 s1, s44, s1
	v_ashrrev_i32_e32 v61, 31, v60
	v_lshl_add_u64 v[32:33], v[60:61], 1, s[0:1]
	s_movk_i32 s0, 0x2000
	v_add_co_u32_e32 v34, vcc, s0, v32
	s_movk_i32 s0, 0x3000
	s_nop 0
	v_addc_co_u32_e32 v35, vcc, 0, v33, vcc
	v_add_co_u32_e32 v36, vcc, s0, v32
	s_movk_i32 s0, 0x4000
	s_nop 0
	v_addc_co_u32_e32 v37, vcc, 0, v33, vcc
	v_add_co_u32_e32 v38, vcc, s0, v32
	s_movk_i32 s0, 0x5000
	s_nop 0
	v_addc_co_u32_e32 v39, vcc, 0, v33, vcc
	v_add_co_u32_e32 v40, vcc, s0, v32
	s_movk_i32 s0, 0x6000
	s_nop 0
	v_addc_co_u32_e32 v41, vcc, 0, v33, vcc
	v_add_co_u32_e32 v42, vcc, s0, v32
	s_movk_i32 s0, 0x7000
	s_nop 0
	v_addc_co_u32_e32 v43, vcc, 0, v33, vcc
	v_add_co_u32_e32 v44, vcc, s0, v32
	s_mov_b32 s0, 0x8000
	s_nop 0
	v_addc_co_u32_e32 v45, vcc, 0, v33, vcc
	v_add_co_u32_e32 v46, vcc, s0, v32
	s_mov_b32 s0, 0x9000
	s_nop 0
	v_addc_co_u32_e32 v47, vcc, 0, v33, vcc
	v_add_co_u32_e32 v48, vcc, s0, v32
	s_mov_b32 s0, 0xa000
	s_nop 0
	v_addc_co_u32_e32 v49, vcc, 0, v33, vcc
	v_add_co_u32_e32 v50, vcc, s0, v32
	s_mov_b32 s0, 0xb000
	s_nop 0
	v_addc_co_u32_e32 v51, vcc, 0, v33, vcc
	v_add_co_u32_e32 v52, vcc, s0, v32
	s_mov_b32 s0, 0xc000
	s_nop 0
	v_addc_co_u32_e32 v53, vcc, 0, v33, vcc
	v_add_co_u32_e32 v54, vcc, s0, v32
	s_mov_b32 s0, 0xd000
	s_nop 0
	v_addc_co_u32_e32 v55, vcc, 0, v33, vcc
	v_add_co_u32_e32 v56, vcc, s0, v32
	s_mov_b32 s0, 0xe000
	s_nop 0
	v_addc_co_u32_e32 v57, vcc, 0, v33, vcc
	v_add_co_u32_e32 v58, vcc, s0, v32
	s_mov_b32 s0, 0xf000
	s_nop 0
	v_addc_co_u32_e32 v59, vcc, 0, v33, vcc
	v_add_co_u32_e32 v62, vcc, s0, v32
	s_mov_b32 s0, 0x10000
	s_nop 0
	v_addc_co_u32_e32 v63, vcc, 0, v33, vcc
	v_add_co_u32_e32 v64, vcc, s0, v32
	s_mov_b32 s0, 0x11000
	s_nop 0
	v_addc_co_u32_e32 v65, vcc, 0, v33, vcc
	v_add_co_u32_e32 v110, vcc, s0, v32
	s_mov_b32 s0, 0x12000
	s_nop 0
	v_addc_co_u32_e32 v111, vcc, 0, v33, vcc
	v_add_co_u32_e32 v112, vcc, s0, v32
	s_mov_b32 s0, 0x14000
	s_nop 0
	v_addc_co_u32_e32 v113, vcc, 0, v33, vcc
	v_add_co_u32_e32 v114, vcc, s0, v32
	s_movk_i32 s0, 0x1000
	s_nop 0
	v_addc_co_u32_e32 v115, vcc, 0, v33, vcc
	global_load_dword v136, v[32:33], off
	global_load_dword v177, v[32:33], off offset:2048
	global_load_dword v181, v[34:35], off offset:2048
	global_load_dword v180, v[38:39], off offset:2048
	global_load_dword v184, v[42:43], off offset:2048
	global_load_dword v183, v[46:47], off offset:2048
	global_load_dword v186, v[50:51], off offset:2048
	global_load_dword v185, v[54:55], off offset:2048
	v_add_co_u32_e32 v34, vcc, s0, v32
	s_nop 1
	v_addc_co_u32_e32 v35, vcc, 0, v33, vcc
	v_add_co_u32_e32 v38, vcc, 0x13000, v32
	s_nop 1
	v_addc_co_u32_e32 v39, vcc, 0, v33, vcc
	global_load_dword v178, v[112:113], off
	global_load_dword v182, v[114:115], off
	global_load_dword v187, v[58:59], off offset:2048
	global_load_dword v189, v[114:115], off offset:2048
	global_load_dword v191, v[34:35], off
	global_load_dword v200, v[38:39], off
	global_load_dword v190, v[112:113], off offset:2048
	global_load_dword v188, v[64:65], off offset:2048
	global_load_dword v159, v[48:49], off offset:-4096
	global_load_dword v158, v[52:53], off offset:-4096
	global_load_dword v176, v[56:57], off offset:-4096
	global_load_dword v161, v[62:63], off offset:-4096
	global_load_dword v198, v[56:57], off
	global_load_dword v196, v[52:53], off
	global_load_dword v197, v[48:49], off
	global_load_dword v194, v[44:45], off
	global_load_dword v179, v[110:111], off offset:-4096
	global_load_dword v201, v[110:111], off
	global_load_dword v199, v[62:63], off
	v_add_u32_e32 v34, s42, v67
	v_ashrrev_i32_e32 v35, 31, v34
	v_add_co_u32_e32 v32, vcc, 0x15000, v32
	v_lshlrev_b64 v[34:35], 6, v[34:35]
	s_nop 0
	v_addc_co_u32_e32 v33, vcc, 0, v33, vcc
	v_lshl_add_u64 v[34:35], s[6:7], 0, v[34:35]
	global_load_dword v157, v[36:37], off offset:-4096
	global_load_dword v156, v[40:41], off offset:-4096
	global_load_dword v160, v[44:45], off offset:-4096
	global_load_dword v195, v[40:41], off
	global_load_dword v193, v[36:37], off
	global_load_dword v202, v[32:33], off
	global_load_dword v203, v[34:35], off
	global_load_dword v204, v[34:35], off offset:32
